# phase 4: blocks with bit3 of block id set walk their tiles in rotated order (q/kv first, LoRA last) so store-bound and MFMA-bound tiles overlap
# baseline (speedup 1.0000x reference)
; DI void phase4(const Params& P, unsigned char* lds) {
;   const int nl = 4 * 66 * 2, nq = 64 * 3, nkv = 66 * 4;
;   for (int it = blockIdx.x; it < nl + nq + nkv; it += gridDim.x) {
;     int r = it;
;     if (r < nl) { const int g = r / 132, rr = r % 132, tm = rr >> 1, tn = rr & 1; const int d = g & 1, isA = g >> 1;
;       GemmDesc gd{(const bf16_t*)(P.ws + OFF_LW) + g * 64, 256, (const bf16_t*)(P.ws + OFF_WL_T) + (size_t)g * 512 * 64, 64, 64};
;       EpiLora e{(bf16_t*)(P.ws + (isA ? OFF_A : OFF_E) + d * SZ_ARR), (isA ? P.rw_a0 : P.rw_w0) + d * 512, isA};
;       gemm_tile(gd, tm * BM, tn * BN, lds, e); continue; }
.LBB0_752:
	s_cmp_lt_i32 s96, 5
	s_waitcnt lgkmcnt(0)
	s_cselect_b64 s[0:1], -1, 0
	s_cmp_gt_i32 s97, 4
	s_cselect_b64 s[2:3], -1, 0
	s_and_b64 s[0:1], s[0:1], s[2:3]
	s_andn2_b64 vcc, exec, s[0:1]
	s_cbranch_vccnz .LBB0_1106
	s_mov_b32 s33, s76
	s_cmpk_gt_i32 s76, 0x3d7
	s_cbranch_scc1 .LBB0_1052
	v_readlane_b32 s0, v243, 34
	v_readlane_b32 s1, v243, 35
	s_add_u32 s30, s0, 0xd8
	s_addc_u32 s31, s1, 0
	s_add_u32 s34, s94, 0x66c8000
	s_addc_u32 s35, s95, 0
	s_add_u32 s36, s94, 0x9a0000
	s_addc_u32 s37, s95, 0
	s_add_u32 s38, s94, 0xbe70000
	s_addc_u32 s39, s95, 0
	s_add_u32 s40, s94, 0xcef0000
	s_addc_u32 s41, s95, 0
	s_add_u32 s48, s94, 0x5a68000
	s_addc_u32 s49, s95, 0
	s_add_u32 s50, s94, 0x910000
	s_addc_u32 s51, s95, 0
	s_add_u32 s52, s92, 0x2000000
	s_addc_u32 s53, s93, 0
	s_add_u32 s3, s94, 0x6f08000
	s_addc_u32 s54, s95, 0
	s_add_u32 s55, s94, 0xa20000
	v_mbcnt_lo_u32_b32 v0, -1, 0
	s_addc_u32 s56, s95, 0
	s_movk_i32 s46, 0x300
	v_mov_b32_e32 v149, 0
	s_movk_i32 s62, 0x90
	s_mov_b32 s63, 0x12000
	s_mov_b32 s64, 0x8000
	s_mov_b32 s65, 0x10000
	s_mov_b32 s66, 0x18000
	s_movk_i32 s67, 0x4000
	s_movk_i32 s47, 0x1f84
	s_movk_i32 s69, 0x3ff8
	s_movk_i32 s58, 0x1f8c
	s_movk_i32 s71, 0x3ff0
	s_movk_i32 s59, 0x1f94
	s_movk_i32 s73, 0x3fe8
	s_movk_i32 s75, 0x3fff
	s_movk_i32 s77, 0x3ffe
	s_movk_i32 s79, 0x3ffd
	s_movk_i32 s81, 0x3ff7
	s_movk_i32 s83, 0x3ff6
	s_movk_i32 s85, 0x3ff5
	s_movk_i32 s87, 0x3fef
	s_movk_i32 s89, 0x3fee
	s_movk_i32 s91, 0x3fed
	s_movk_i32 s68, 0x3fe7
	s_movk_i32 s72, 0x3fe6
	s_movk_i32 s76, 0x3fe5
	s_movk_i32 s80, 0x4200
	s_movk_i32 s82, 0x2100
	v_mov_b32_e32 v166, 0x48
	v_mov_b32_e32 v167, 0x50
	v_mov_b32_e32 v168, 0x58
	v_mov_b32_e32 v169, 0x41
	v_mov_b32_e32 v170, 0x42
	v_mov_b32_e32 v171, 0x43
	v_mov_b32_e32 v172, 0x49
	v_mov_b32_e32 v173, 0x4a
	v_mov_b32_e32 v174, 0x4b
	v_mov_b32_e32 v175, 0x51
	v_mov_b32_e32 v176, 0x52
	v_mov_b32_e32 v177, 0x53
	v_mov_b32_e32 v178, 0x59
	v_mov_b32_e32 v179, 0x5a
	v_mov_b32_e32 v180, 0x5b
	v_mov_b32_e32 v181, 0x60
	v_mov_b32_e32 v182, 0x68
	v_mov_b32_e32 v183, 0x70
	v_mov_b32_e32 v184, 0x78
	v_mov_b32_e32 v185, 0x61
	v_mov_b32_e32 v186, 0x62
	v_mov_b32_e32 v187, 0x63
	v_mov_b32_e32 v188, 0x69
	v_mov_b32_e32 v189, 0x6a
	v_mov_b32_e32 v190, 0x6b
	v_mov_b32_e32 v191, 0x71
	v_mov_b32_e32 v192, 0x72
	v_mov_b32_e32 v193, 0x73
	v_mov_b32_e32 v194, 0x79
	v_mov_b32_e32 v195, 0x7a
	v_mov_b32_e32 v196, 0x7b
	v_mov_b32_e32 v197, 0x42800000
	v_not_b32_e32 v198, 63
	v_mbcnt_hi_u32_b32 v199, -1, v0
	v_mov_b32_e32 v200, 0x3f1b4598
	s_movk_i32 s70, 0x1ffe
	s_movk_i32 s74, 0x1fff
	s_mov_b32 s78, 0xc000
	s_mov_b32 s84, 0x24000
	s_movk_i32 s86, 0xc0
	s_movk_i32 s57, 0xffa0
	s_movk_i32 s90, 0x4f
	s_mov_b32 s44, 0
	s_bfe_u32 s45, s33, 0x10003
	s_lshl_b32 s45, s45, 9
	s_add_u32 s2, s33, s45
	s_branch .LBB0_756
.LBB0_755:
.Lp4_next:
	s_add_u32 s44, s44, 1
	s_cmp_ge_u32 s44, 4
	s_cbranch_scc1 .LBB0_1052
	s_add_u32 s2, s2, 0x100
	s_sub_u32 s45, s2, 0x400
	s_cmp_ge_u32 s2, 0x400
	s_cselect_b32 s2, s45, s2
	s_cmpk_ge_u32 s2, 0x3d8
	s_cbranch_scc1 .Lp4_next
